# LayerNorm epilogue row statistics: cross-lane sums via v_permlane16/32_swap instead of 32 ds_bpermute round trips (on the stack)
# speedup vs baseline: 1.0126x; 1.0052x over previous
.LBB0_693:
	v_pk_add_f32 v[190:191], v[114:115], v[142:143]
	v_pk_add_f32 v[196:197], v[112:113], v[140:141]
	v_pk_add_f32 v[142:143], v[102:103], v[142:143]
	v_pk_add_f32 v[140:141], v[100:101], v[140:141]
	v_pk_add_f32 v[102:103], v[106:107], v[138:139]
	v_pk_add_f32 v[100:101], v[104:105], v[136:137]
	v_pk_add_f32 v[104:105], v[126:127], v[134:135]
	v_pk_add_f32 v[106:107], v[124:125], v[132:133]
	v_pk_add_f32 v[112:113], v[122:123], v[130:131]
	v_pk_add_f32 v[114:115], v[120:121], v[128:129]
	s_mov_b32 s12, 0x3fd744fd
	s_waitcnt vmcnt(6)
	v_pk_fma_f32 v[120:121], v[168:169], s[12:13], v[114:115] op_sel_hi:[1,0,1]
	v_pk_fma_f32 v[122:123], v[170:171], s[12:13], v[112:113] op_sel_hi:[1,0,1]
	v_pk_fma_f32 v[112:113], v[164:165], s[12:13], v[106:107] op_sel_hi:[1,0,1]
	v_pk_fma_f32 v[114:115], v[166:167], s[12:13], v[104:105] op_sel_hi:[1,0,1]
	v_mov_b32_e32 v104, v73
	v_mov_b32_e32 v105, v74
	v_mov_b32_e32 v106, v72
	v_mov_b32_e32 v107, v75
	v_pk_add_f32 v[132:133], v[116:117], v[132:133]
	v_pk_add_f32 v[104:105], v[104:105], v[106:107]
	v_mov_b32_e32 v106, v69
	v_mov_b32_e32 v107, v70
	v_mov_b32_e32 v116, v68
	v_mov_b32_e32 v117, v71
	v_pk_add_f32 v[106:107], v[106:107], v[116:117]
	v_add_f32_e32 v104, v104, v105
	v_pk_add_f32 v[106:107], v[106:107], v[106:107] op_sel_hi:[0,1]
	v_pk_add_f32 v[134:135], v[118:119], v[134:135]
	v_add_f32_e32 v105, 0, v104
	v_add_f32_e32 v117, v20, v21
	v_add_f32_e32 v119, v22, v23
	v_mov_b32_e32 v116, v16
	v_mov_b32_e32 v118, v17
	v_mov_b32_e32 v106, v18
	v_mov_b32_e32 v104, v19
	v_pk_add_f32 v[116:117], v[116:117], v[118:119]
	v_pk_add_f32 v[104:105], v[106:107], v[104:105]
	v_pk_add_f32 v[108:109], v[108:109], v[128:129]
	v_pk_add_f32 v[104:105], v[116:117], v[104:105]
	v_pk_add_f32 v[110:111], v[110:111], v[130:131]
	v_add_f32_e32 v104, v104, v105
	v_mov_b32_e32 v105, v104
	s_nop 1
	v_permlane16_swap_b32_e32 v104, v105
	v_pk_add_f32 v[98:99], v[98:99], v[138:139]
	v_pk_add_f32 v[96:97], v[96:97], v[136:137]
	s_waitcnt vmcnt(4)
	v_pk_fma_f32 v[100:101], v[172:173], s[12:13], v[100:101] op_sel_hi:[1,0,1]
	v_pk_fma_f32 v[102:103], v[174:175], s[12:13], v[102:103] op_sel_hi:[1,0,1]
	s_waitcnt lgkmcnt(0)
	v_add_f32_e32 v104, v104, v105
	v_mov_b32_e32 v105, v104
	s_nop 1
	v_permlane32_swap_b32_e32 v104, v105
	v_pk_fma_f32 v[124:125], v[144:145], s[12:13], v[196:197] op_sel_hi:[1,0,1]
	v_pk_fma_f32 v[126:127], v[146:147], s[12:13], v[190:191] op_sel_hi:[1,0,1]
	s_waitcnt vmcnt(2)
	v_pk_fma_f32 v[116:117], v[160:161], s[12:13], v[108:109] op_sel_hi:[1,0,1]
	v_pk_fma_f32 v[118:119], v[162:163], s[12:13], v[110:111] op_sel_hi:[1,0,1]
	s_waitcnt lgkmcnt(0)
	v_add_f32_e32 v128, v104, v105
	v_fmamk_f32 v105, v128, 0xbc800000, v75
	v_fmamk_f32 v107, v128, 0xbc800000, v73
	v_fmamk_f32 v104, v128, 0xbc800000, v74
	v_fmamk_f32 v106, v128, 0xbc800000, v72
	v_mul_f32_e32 v107, v107, v107
	v_mul_f32_e32 v105, v105, v105
	v_fmac_f32_e32 v107, v106, v106
	v_fmac_f32_e32 v105, v104, v104
	v_fmamk_f32 v106, v128, 0xbc800000, v71
	v_fmamk_f32 v129, v128, 0xbc800000, v69
	v_add_f32_e32 v104, v107, v105
	v_fmamk_f32 v105, v128, 0xbc800000, v70
	v_fmamk_f32 v107, v128, 0xbc800000, v68
	v_mul_f32_e32 v129, v129, v129
	v_mul_f32_e32 v106, v106, v106
	v_fmac_f32_e32 v129, v107, v107
	v_fmac_f32_e32 v106, v105, v105
	v_add_f32_e32 v105, v129, v106
	v_fmamk_f32 v106, v128, 0xbc800000, v23
	v_fmamk_f32 v129, v128, 0xbc800000, v21
	v_add_f32_e32 v104, v104, v105
	v_fmamk_f32 v105, v128, 0xbc800000, v22
	v_fmamk_f32 v107, v128, 0xbc800000, v20
	v_mul_f32_e32 v129, v129, v129
	v_mul_f32_e32 v106, v106, v106
	v_fmac_f32_e32 v129, v107, v107
	v_fmac_f32_e32 v106, v105, v105
	v_add_f32_e32 v105, v129, v106
	v_fmamk_f32 v106, v128, 0xbc800000, v19
	v_fmamk_f32 v129, v128, 0xbc800000, v17
	v_add_f32_e32 v104, v105, v104
	v_fmamk_f32 v105, v128, 0xbc800000, v18
	v_fmamk_f32 v107, v128, 0xbc800000, v16
	v_mul_f32_e32 v129, v129, v129
	v_mul_f32_e32 v106, v106, v106
	v_fmac_f32_e32 v129, v107, v107
	v_fmac_f32_e32 v106, v105, v105
	v_add_f32_e32 v105, v129, v106
	v_add_f32_e32 v129, v105, v104
	v_mov_b32_e32 v130, v129
	s_nop 1
	v_permlane16_swap_b32_e32 v129, v130
	v_pk_fma_f32 v[108:109], v[156:157], s[12:13], v[132:133] op_sel_hi:[1,0,1]
	v_pk_fma_f32 v[110:111], v[158:159], s[12:13], v[134:135] op_sel_hi:[1,0,1]
	s_waitcnt vmcnt(0)
	v_pk_fma_f32 v[96:97], v[152:153], s[12:13], v[96:97] op_sel_hi:[1,0,1]
	v_pk_fma_f32 v[98:99], v[154:155], s[12:13], v[98:99] op_sel_hi:[1,0,1]
	s_waitcnt lgkmcnt(0)
	v_add_f32_e32 v129, v129, v130
	v_mov_b32_e32 v130, v129
	s_nop 1
	v_permlane32_swap_b32_e32 v129, v130
	v_pk_fma_f32 v[104:105], v[148:149], s[12:13], v[140:141] op_sel_hi:[1,0,1]
	v_pk_fma_f32 v[106:107], v[150:151], s[12:13], v[142:143] op_sel_hi:[1,0,1]
	s_nop 0
	s_and_saveexec_b64 s[12:13], s[4:5]
	s_xor_b64 s[12:13], exec, s[12:13]
	s_cbranch_execz .LBB0_695
	v_mul_f32_e32 v128, 0x3c800000, v128
	s_waitcnt lgkmcnt(0)
	v_add_f32_e32 v129, v129, v130
	ds_write_b64 v233, v[128:129]
.LBB0_695:
	s_or_b64 exec, exec, s[12:13]
	v_mov_b32_e32 v128, v13
	v_mov_b32_e32 v129, v14
	s_waitcnt lgkmcnt(0)
	v_mov_b32_e32 v130, v12
	v_mov_b32_e32 v131, v15
	v_pk_add_f32 v[128:129], v[128:129], v[130:131]
	v_mov_b32_e32 v130, v9
	v_mov_b32_e32 v131, v10
	v_mov_b32_e32 v132, v8
	v_mov_b32_e32 v133, v11
	v_pk_add_f32 v[130:131], v[130:131], v[132:133]
	v_add_f32_e32 v128, v128, v129
	v_pk_add_f32 v[130:131], v[130:131], v[130:131] op_sel_hi:[0,1]
	v_add_f32_e32 v129, 0, v128
	v_add_f32_e32 v133, v4, v5
	v_add_f32_e32 v135, v6, v7
	v_mov_b32_e32 v132, v0
	v_mov_b32_e32 v134, v1
	v_mov_b32_e32 v130, v2
	v_mov_b32_e32 v128, v3
	v_pk_add_f32 v[132:133], v[132:133], v[134:135]
	v_pk_add_f32 v[128:129], v[130:131], v[128:129]
	s_nop 0
	v_pk_add_f32 v[128:129], v[132:133], v[128:129]
	s_nop 0
	v_add_f32_e32 v128, v128, v129
	v_mov_b32_e32 v129, v128
	s_nop 1
	v_permlane16_swap_b32_e32 v128, v129
	s_waitcnt lgkmcnt(0)
	v_add_f32_e32 v128, v128, v129
	v_mov_b32_e32 v129, v128
	s_nop 1
	v_permlane32_swap_b32_e32 v128, v129
	s_waitcnt lgkmcnt(0)
	v_add_f32_e32 v128, v128, v129
	v_fmamk_f32 v130, v128, 0xbc800000, v15
	v_fmamk_f32 v132, v128, 0xbc800000, v13
	v_fmamk_f32 v129, v128, 0xbc800000, v14
	v_fmamk_f32 v131, v128, 0xbc800000, v12
	v_mul_f32_e32 v132, v132, v132
	v_mul_f32_e32 v130, v130, v130
	v_fmac_f32_e32 v132, v131, v131
	v_fmac_f32_e32 v130, v129, v129
	v_fmamk_f32 v131, v128, 0xbc800000, v11
	v_fmamk_f32 v133, v128, 0xbc800000, v9
	v_add_f32_e32 v129, v132, v130
	v_fmamk_f32 v130, v128, 0xbc800000, v10
	v_fmamk_f32 v132, v128, 0xbc800000, v8
	v_mul_f32_e32 v133, v133, v133
	v_mul_f32_e32 v131, v131, v131
	v_fmac_f32_e32 v133, v132, v132
	v_fmac_f32_e32 v131, v130, v130
	v_add_f32_e32 v130, v133, v131
	v_fmamk_f32 v131, v128, 0xbc800000, v7
	v_fmamk_f32 v133, v128, 0xbc800000, v5
	v_add_f32_e32 v129, v129, v130
	v_fmamk_f32 v130, v128, 0xbc800000, v6
	v_fmamk_f32 v132, v128, 0xbc800000, v4
	v_mul_f32_e32 v133, v133, v133
	v_mul_f32_e32 v131, v131, v131
	v_fmac_f32_e32 v133, v132, v132
	v_fmac_f32_e32 v131, v130, v130
	v_add_f32_e32 v130, v133, v131
	v_fmamk_f32 v131, v128, 0xbc800000, v3
	v_fmamk_f32 v133, v128, 0xbc800000, v1
	v_add_f32_e32 v129, v130, v129
	v_fmamk_f32 v130, v128, 0xbc800000, v2
	v_fmamk_f32 v132, v128, 0xbc800000, v0
	v_mul_f32_e32 v133, v133, v133
	v_mul_f32_e32 v131, v131, v131
	v_fmac_f32_e32 v133, v132, v132
	v_fmac_f32_e32 v131, v130, v130
	v_add_f32_e32 v130, v133, v131
	v_add_f32_e32 v129, v130, v129
	v_mov_b32_e32 v130, v129
	s_nop 1
	v_permlane16_swap_b32_e32 v129, v130
	s_waitcnt lgkmcnt(0)
	v_add_f32_e32 v129, v129, v130
	v_mov_b32_e32 v130, v129
	s_nop 1
	v_permlane32_swap_b32_e32 v129, v130
	s_and_saveexec_b64 s[12:13], s[4:5]
	s_cbranch_execz .LBB0_697
	v_mul_f32_e32 v128, 0x3c800000, v128
	s_waitcnt lgkmcnt(0)
	v_add_f32_e32 v129, v129, v130
	ds_write_b64 v233, v[128:129] offset:512
.LBB0_697:
	s_or_b64 exec, exec, s[12:13]
	v_mov_b32_e32 v128, v61
	v_mov_b32_e32 v129, v62
	s_waitcnt lgkmcnt(0)
	v_mov_b32_e32 v130, v60
	v_mov_b32_e32 v131, v63
	v_pk_add_f32 v[128:129], v[128:129], v[130:131]
	v_mov_b32_e32 v130, v57
	v_mov_b32_e32 v131, v58
	v_mov_b32_e32 v132, v56
	v_mov_b32_e32 v133, v59
	v_pk_add_f32 v[130:131], v[130:131], v[132:133]
	v_add_f32_e32 v128, v128, v129
	v_pk_add_f32 v[130:131], v[130:131], v[130:131] op_sel_hi:[0,1]
	v_add_f32_e32 v129, 0, v128
	v_add_f32_e32 v133, v44, v45
	v_add_f32_e32 v135, v46, v47
	v_mov_b32_e32 v132, v40
	v_mov_b32_e32 v134, v41
	v_mov_b32_e32 v130, v42
	v_mov_b32_e32 v128, v43
	v_pk_add_f32 v[132:133], v[132:133], v[134:135]
	v_pk_add_f32 v[128:129], v[130:131], v[128:129]
	s_nop 0
	v_pk_add_f32 v[128:129], v[132:133], v[128:129]
	s_nop 0
	v_add_f32_e32 v128, v128, v129
	v_mov_b32_e32 v129, v128
	s_nop 1
	v_permlane16_swap_b32_e32 v128, v129
	s_waitcnt lgkmcnt(0)
	v_add_f32_e32 v128, v128, v129
	v_mov_b32_e32 v129, v128
	s_nop 1
	v_permlane32_swap_b32_e32 v128, v129
	s_waitcnt lgkmcnt(0)
	v_add_f32_e32 v128, v128, v129
	v_fmamk_f32 v130, v128, 0xbc800000, v63
	v_fmamk_f32 v132, v128, 0xbc800000, v61
	v_fmamk_f32 v129, v128, 0xbc800000, v62
	v_fmamk_f32 v131, v128, 0xbc800000, v60
	v_mul_f32_e32 v132, v132, v132
	v_mul_f32_e32 v130, v130, v130
	v_fmac_f32_e32 v132, v131, v131
	v_fmac_f32_e32 v130, v129, v129
	v_fmamk_f32 v131, v128, 0xbc800000, v59
	v_fmamk_f32 v133, v128, 0xbc800000, v57
	v_add_f32_e32 v129, v132, v130
	v_fmamk_f32 v130, v128, 0xbc800000, v58
	v_fmamk_f32 v132, v128, 0xbc800000, v56
	v_mul_f32_e32 v133, v133, v133
	v_mul_f32_e32 v131, v131, v131
	v_fmac_f32_e32 v133, v132, v132
	v_fmac_f32_e32 v131, v130, v130
	v_add_f32_e32 v130, v133, v131
	v_fmamk_f32 v131, v128, 0xbc800000, v47
	v_fmamk_f32 v133, v128, 0xbc800000, v45
	v_add_f32_e32 v129, v129, v130
	v_fmamk_f32 v130, v128, 0xbc800000, v46
	v_fmamk_f32 v132, v128, 0xbc800000, v44
	v_mul_f32_e32 v133, v133, v133
	v_mul_f32_e32 v131, v131, v131
	v_fmac_f32_e32 v133, v132, v132
	v_fmac_f32_e32 v131, v130, v130
	v_add_f32_e32 v130, v133, v131
	v_fmamk_f32 v131, v128, 0xbc800000, v43
	v_fmamk_f32 v133, v128, 0xbc800000, v41
	v_add_f32_e32 v129, v130, v129
	v_fmamk_f32 v130, v128, 0xbc800000, v42
	v_fmamk_f32 v132, v128, 0xbc800000, v40
	v_mul_f32_e32 v133, v133, v133
	v_mul_f32_e32 v131, v131, v131
	v_fmac_f32_e32 v133, v132, v132
	v_fmac_f32_e32 v131, v130, v130
	v_add_f32_e32 v130, v133, v131
	v_add_f32_e32 v129, v130, v129
	v_mov_b32_e32 v130, v129
	s_nop 1
	v_permlane16_swap_b32_e32 v129, v130
	s_waitcnt lgkmcnt(0)
	v_add_f32_e32 v129, v129, v130
	v_mov_b32_e32 v130, v129
	s_nop 1
	v_permlane32_swap_b32_e32 v129, v130
	s_and_saveexec_b64 s[12:13], s[4:5]
	s_cbranch_execz .LBB0_699
	v_mul_f32_e32 v128, 0x3c800000, v128
	s_waitcnt lgkmcnt(0)
	v_add_f32_e32 v129, v129, v130
	ds_write_b64 v233, v[128:129] offset:1024
.LBB0_699:
	s_or_b64 exec, exec, s[12:13]
	v_mov_b32_e32 v128, v37
	v_mov_b32_e32 v129, v38
	s_waitcnt lgkmcnt(0)
	v_mov_b32_e32 v130, v36
	v_mov_b32_e32 v131, v39
	v_pk_add_f32 v[128:129], v[128:129], v[130:131]
	v_mov_b32_e32 v130, v33
	v_mov_b32_e32 v131, v34
	v_mov_b32_e32 v132, v32
	v_mov_b32_e32 v133, v35
	v_pk_add_f32 v[130:131], v[130:131], v[132:133]
	v_add_f32_e32 v128, v128, v129
	v_pk_add_f32 v[130:131], v[130:131], v[130:131] op_sel_hi:[0,1]
	v_add_f32_e32 v129, 0, v128
	v_add_f32_e32 v133, v28, v29
	v_add_f32_e32 v135, v30, v31
	v_mov_b32_e32 v132, v24
	v_mov_b32_e32 v134, v25
	v_mov_b32_e32 v130, v26
	v_mov_b32_e32 v128, v27
	v_pk_add_f32 v[132:133], v[132:133], v[134:135]
	v_pk_add_f32 v[128:129], v[130:131], v[128:129]
	s_nop 0
	v_pk_add_f32 v[128:129], v[132:133], v[128:129]
	s_nop 0
	v_add_f32_e32 v128, v128, v129
	v_mov_b32_e32 v129, v128
	s_nop 1
	v_permlane16_swap_b32_e32 v128, v129
	s_waitcnt lgkmcnt(0)
	v_add_f32_e32 v128, v128, v129
	v_mov_b32_e32 v129, v128
	s_nop 1
	v_permlane32_swap_b32_e32 v128, v129
	s_waitcnt lgkmcnt(0)
	v_add_f32_e32 v128, v128, v129
	v_fmamk_f32 v130, v128, 0xbc800000, v39
	v_fmamk_f32 v132, v128, 0xbc800000, v37
	v_fmamk_f32 v129, v128, 0xbc800000, v38
	v_fmamk_f32 v131, v128, 0xbc800000, v36
	v_mul_f32_e32 v132, v132, v132
	v_mul_f32_e32 v130, v130, v130
	v_fmac_f32_e32 v132, v131, v131
	v_fmac_f32_e32 v130, v129, v129
	v_fmamk_f32 v131, v128, 0xbc800000, v35
	v_fmamk_f32 v133, v128, 0xbc800000, v33
	v_add_f32_e32 v129, v132, v130
	v_fmamk_f32 v130, v128, 0xbc800000, v34
	v_fmamk_f32 v132, v128, 0xbc800000, v32
	v_mul_f32_e32 v133, v133, v133
	v_mul_f32_e32 v131, v131, v131
	v_fmac_f32_e32 v133, v132, v132
	v_fmac_f32_e32 v131, v130, v130
	v_add_f32_e32 v130, v133, v131
	v_fmamk_f32 v131, v128, 0xbc800000, v31
	v_fmamk_f32 v133, v128, 0xbc800000, v29
	v_add_f32_e32 v129, v129, v130
	v_fmamk_f32 v130, v128, 0xbc800000, v30
	v_fmamk_f32 v132, v128, 0xbc800000, v28
	v_mul_f32_e32 v133, v133, v133
	v_mul_f32_e32 v131, v131, v131
	v_fmac_f32_e32 v133, v132, v132
	v_fmac_f32_e32 v131, v130, v130
	v_add_f32_e32 v130, v133, v131
	v_fmamk_f32 v131, v128, 0xbc800000, v27
	v_fmamk_f32 v133, v128, 0xbc800000, v25
	v_add_f32_e32 v129, v130, v129
	v_fmamk_f32 v130, v128, 0xbc800000, v26
	v_fmamk_f32 v132, v128, 0xbc800000, v24
	v_mul_f32_e32 v133, v133, v133
	v_mul_f32_e32 v131, v131, v131
	v_fmac_f32_e32 v133, v132, v132
	v_fmac_f32_e32 v131, v130, v130
	v_add_f32_e32 v130, v133, v131
	v_add_f32_e32 v129, v130, v129
	v_mov_b32_e32 v130, v129
	s_nop 1
	v_permlane16_swap_b32_e32 v129, v130
	s_waitcnt lgkmcnt(0)
	v_add_f32_e32 v129, v129, v130
	v_mov_b32_e32 v130, v129
	s_nop 1
	v_permlane32_swap_b32_e32 v129, v130
	s_and_saveexec_b64 s[12:13], s[4:5]
	s_cbranch_execz .LBB0_701
	v_mul_f32_e32 v128, 0x3c800000, v128
	s_waitcnt lgkmcnt(0)
	v_add_f32_e32 v129, v129, v130
	ds_write_b64 v233, v[128:129] offset:1536
.LBB0_701:
	s_or_b64 exec, exec, s[12:13]
	v_mov_b32_e32 v128, v93
	v_mov_b32_e32 v129, v94
	s_waitcnt lgkmcnt(0)
	v_mov_b32_e32 v130, v92
	v_mov_b32_e32 v131, v95
	v_pk_add_f32 v[128:129], v[128:129], v[130:131]
	v_mov_b32_e32 v130, v89
	v_mov_b32_e32 v131, v90
	v_mov_b32_e32 v132, v88
	v_mov_b32_e32 v133, v91
	v_pk_add_f32 v[130:131], v[130:131], v[132:133]
	v_add_f32_e32 v128, v128, v129
	v_pk_add_f32 v[130:131], v[130:131], v[130:131] op_sel_hi:[0,1]
	v_add_f32_e32 v129, 0, v128
	v_add_f32_e32 v133, v84, v85
	v_add_f32_e32 v135, v86, v87
	v_mov_b32_e32 v132, v80
	v_mov_b32_e32 v134, v81
	v_mov_b32_e32 v130, v82
	v_mov_b32_e32 v128, v83
	v_pk_add_f32 v[132:133], v[132:133], v[134:135]
	v_pk_add_f32 v[128:129], v[130:131], v[128:129]
	s_nop 0
	v_pk_add_f32 v[128:129], v[132:133], v[128:129]
	s_nop 0
	v_add_f32_e32 v128, v128, v129
	v_mov_b32_e32 v129, v128
	s_nop 1
	v_permlane16_swap_b32_e32 v128, v129
	s_waitcnt lgkmcnt(0)
	v_add_f32_e32 v128, v128, v129
	v_mov_b32_e32 v129, v128
	s_nop 1
	v_permlane32_swap_b32_e32 v128, v129
	s_waitcnt lgkmcnt(0)
	v_add_f32_e32 v128, v128, v129
	v_fmamk_f32 v130, v128, 0xbc800000, v95
	v_fmamk_f32 v132, v128, 0xbc800000, v93
	v_fmamk_f32 v129, v128, 0xbc800000, v94
	v_fmamk_f32 v131, v128, 0xbc800000, v92
	v_mul_f32_e32 v132, v132, v132
	v_mul_f32_e32 v130, v130, v130
	v_fmac_f32_e32 v132, v131, v131
	v_fmac_f32_e32 v130, v129, v129
	v_fmamk_f32 v131, v128, 0xbc800000, v91
	v_fmamk_f32 v133, v128, 0xbc800000, v89
	v_add_f32_e32 v129, v132, v130
	v_fmamk_f32 v130, v128, 0xbc800000, v90
	v_fmamk_f32 v132, v128, 0xbc800000, v88
	v_mul_f32_e32 v133, v133, v133
	v_mul_f32_e32 v131, v131, v131
	v_fmac_f32_e32 v133, v132, v132
	v_fmac_f32_e32 v131, v130, v130
	v_add_f32_e32 v130, v133, v131
	v_fmamk_f32 v131, v128, 0xbc800000, v87
	v_fmamk_f32 v133, v128, 0xbc800000, v85
	v_add_f32_e32 v129, v129, v130
	v_fmamk_f32 v130, v128, 0xbc800000, v86
	v_fmamk_f32 v132, v128, 0xbc800000, v84
	v_mul_f32_e32 v133, v133, v133
	v_mul_f32_e32 v131, v131, v131
	v_fmac_f32_e32 v133, v132, v132
	v_fmac_f32_e32 v131, v130, v130
	v_add_f32_e32 v130, v133, v131
	v_fmamk_f32 v131, v128, 0xbc800000, v83
	v_fmamk_f32 v133, v128, 0xbc800000, v81
	v_add_f32_e32 v129, v130, v129
	v_fmamk_f32 v130, v128, 0xbc800000, v82
	v_fmamk_f32 v132, v128, 0xbc800000, v80
	v_mul_f32_e32 v133, v133, v133
	v_mul_f32_e32 v131, v131, v131
	v_fmac_f32_e32 v133, v132, v132
	v_fmac_f32_e32 v131, v130, v130
	v_add_f32_e32 v130, v133, v131
	v_add_f32_e32 v129, v130, v129
	v_mov_b32_e32 v130, v129
	s_nop 1
	v_permlane16_swap_b32_e32 v129, v130
	s_waitcnt lgkmcnt(0)
	v_add_f32_e32 v129, v129, v130
	v_mov_b32_e32 v130, v129
	s_nop 1
	v_permlane32_swap_b32_e32 v129, v130
	s_and_saveexec_b64 s[12:13], s[4:5]
	s_cbranch_execz .LBB0_703
	v_mul_f32_e32 v128, 0x3c800000, v128
	s_waitcnt lgkmcnt(0)
	v_add_f32_e32 v129, v129, v130
	ds_write_b64 v233, v[128:129] offset:4096
.LBB0_703:
	s_or_b64 exec, exec, s[12:13]
	v_mov_b32_e32 v128, v77
	v_mov_b32_e32 v129, v78
	s_waitcnt lgkmcnt(0)
	v_mov_b32_e32 v130, v76
	v_mov_b32_e32 v131, v79
	v_pk_add_f32 v[128:129], v[128:129], v[130:131]
	v_mov_b32_e32 v130, v65
	v_mov_b32_e32 v131, v66
	v_mov_b32_e32 v132, v64
	v_mov_b32_e32 v133, v67
	v_pk_add_f32 v[130:131], v[130:131], v[132:133]
	v_add_f32_e32 v128, v128, v129
	v_pk_add_f32 v[130:131], v[130:131], v[130:131] op_sel_hi:[0,1]
	v_add_f32_e32 v129, 0, v128
	v_add_f32_e32 v133, v52, v53
	v_add_f32_e32 v135, v54, v55
	v_mov_b32_e32 v132, v48
	v_mov_b32_e32 v134, v49
	v_mov_b32_e32 v130, v50
	v_mov_b32_e32 v128, v51
	v_pk_add_f32 v[132:133], v[132:133], v[134:135]
	v_pk_add_f32 v[128:129], v[130:131], v[128:129]
	s_nop 0
	v_pk_add_f32 v[128:129], v[132:133], v[128:129]
	s_nop 0
	v_add_f32_e32 v128, v128, v129
	v_mov_b32_e32 v129, v128
	s_nop 1
	v_permlane16_swap_b32_e32 v128, v129
	s_waitcnt lgkmcnt(0)
	v_add_f32_e32 v128, v128, v129
	v_mov_b32_e32 v129, v128
	s_nop 1
	v_permlane32_swap_b32_e32 v128, v129
	s_waitcnt lgkmcnt(0)
	v_add_f32_e32 v128, v128, v129
	v_fmamk_f32 v130, v128, 0xbc800000, v79
	v_fmamk_f32 v132, v128, 0xbc800000, v77
	v_fmamk_f32 v129, v128, 0xbc800000, v78
	v_fmamk_f32 v131, v128, 0xbc800000, v76
	v_mul_f32_e32 v132, v132, v132
	v_mul_f32_e32 v130, v130, v130
	v_fmac_f32_e32 v132, v131, v131
	v_fmac_f32_e32 v130, v129, v129
	v_fmamk_f32 v131, v128, 0xbc800000, v67
	v_fmamk_f32 v133, v128, 0xbc800000, v65
	v_add_f32_e32 v129, v132, v130
	v_fmamk_f32 v130, v128, 0xbc800000, v66
	v_fmamk_f32 v132, v128, 0xbc800000, v64
	v_mul_f32_e32 v133, v133, v133
	v_mul_f32_e32 v131, v131, v131
	v_fmac_f32_e32 v133, v132, v132
	v_fmac_f32_e32 v131, v130, v130
	v_add_f32_e32 v130, v133, v131
	v_fmamk_f32 v131, v128, 0xbc800000, v55
	v_fmamk_f32 v133, v128, 0xbc800000, v53
	v_add_f32_e32 v129, v129, v130
	v_fmamk_f32 v130, v128, 0xbc800000, v54
	v_fmamk_f32 v132, v128, 0xbc800000, v52
	v_mul_f32_e32 v133, v133, v133
	v_mul_f32_e32 v131, v131, v131
	v_fmac_f32_e32 v133, v132, v132
	v_fmac_f32_e32 v131, v130, v130
	v_add_f32_e32 v130, v133, v131
	v_fmamk_f32 v131, v128, 0xbc800000, v51
	v_fmamk_f32 v133, v128, 0xbc800000, v49
	v_add_f32_e32 v129, v130, v129
	v_fmamk_f32 v130, v128, 0xbc800000, v50
	v_fmamk_f32 v132, v128, 0xbc800000, v48
	v_mul_f32_e32 v133, v133, v133
	v_mul_f32_e32 v131, v131, v131
	v_fmac_f32_e32 v133, v132, v132
	v_fmac_f32_e32 v131, v130, v130
	v_add_f32_e32 v130, v133, v131
	v_add_f32_e32 v129, v130, v129
	v_mov_b32_e32 v130, v129
	s_nop 1
	v_permlane16_swap_b32_e32 v129, v130
	s_waitcnt lgkmcnt(0)
	v_add_f32_e32 v129, v129, v130
	v_mov_b32_e32 v130, v129
	s_nop 1
	v_permlane32_swap_b32_e32 v129, v130
	s_and_saveexec_b64 s[12:13], s[4:5]
	s_cbranch_execz .LBB0_705
	v_mul_f32_e32 v128, 0x3c800000, v128
	s_waitcnt lgkmcnt(0)
	v_add_f32_e32 v129, v129, v130
	ds_write_b64 v233, v[128:129] offset:4608
.LBB0_705:
	s_or_b64 exec, exec, s[12:13]
	v_mov_b32_e32 v128, v121
	v_mov_b32_e32 v129, v122
	s_waitcnt lgkmcnt(0)
	v_mov_b32_e32 v130, v120
	v_mov_b32_e32 v131, v123
	v_pk_add_f32 v[128:129], v[128:129], v[130:131]
	v_mov_b32_e32 v130, v113
	v_mov_b32_e32 v131, v114
	v_mov_b32_e32 v132, v112
	v_mov_b32_e32 v133, v115
	v_pk_add_f32 v[130:131], v[130:131], v[132:133]
	v_add_f32_e32 v128, v128, v129
	v_pk_add_f32 v[130:131], v[130:131], v[130:131] op_sel_hi:[0,1]
	v_add_f32_e32 v129, 0, v128
	v_add_f32_e32 v133, v100, v101
	v_add_f32_e32 v135, v102, v103
	v_mov_b32_e32 v132, v124
	v_mov_b32_e32 v134, v125
	v_mov_b32_e32 v130, v126
	v_mov_b32_e32 v128, v127
	v_pk_add_f32 v[132:133], v[132:133], v[134:135]
	v_pk_add_f32 v[128:129], v[130:131], v[128:129]
	s_nop 0
	v_pk_add_f32 v[128:129], v[132:133], v[128:129]
	s_nop 0
	v_add_f32_e32 v128, v128, v129
	v_mov_b32_e32 v129, v128
	s_nop 1
	v_permlane16_swap_b32_e32 v128, v129
	s_waitcnt lgkmcnt(0)
	v_add_f32_e32 v128, v128, v129
	v_mov_b32_e32 v129, v128
	s_nop 1
	v_permlane32_swap_b32_e32 v128, v129
	s_waitcnt lgkmcnt(0)
	v_add_f32_e32 v128, v128, v129
	v_fmamk_f32 v130, v128, 0xbc800000, v123
	v_fmamk_f32 v132, v128, 0xbc800000, v121
	v_fmamk_f32 v129, v128, 0xbc800000, v122
	v_fmamk_f32 v131, v128, 0xbc800000, v120
	v_mul_f32_e32 v132, v132, v132
	v_mul_f32_e32 v130, v130, v130
	v_fmac_f32_e32 v132, v131, v131
	v_fmac_f32_e32 v130, v129, v129
	v_fmamk_f32 v131, v128, 0xbc800000, v115
	v_fmamk_f32 v133, v128, 0xbc800000, v113
	v_add_f32_e32 v129, v132, v130
	v_fmamk_f32 v130, v128, 0xbc800000, v114
	v_fmamk_f32 v132, v128, 0xbc800000, v112
	v_mul_f32_e32 v133, v133, v133
	v_mul_f32_e32 v131, v131, v131
	v_fmac_f32_e32 v133, v132, v132
	v_fmac_f32_e32 v131, v130, v130
	v_add_f32_e32 v130, v133, v131
	v_fmamk_f32 v131, v128, 0xbc800000, v103
	v_fmamk_f32 v133, v128, 0xbc800000, v101
	v_add_f32_e32 v129, v129, v130
	v_fmamk_f32 v130, v128, 0xbc800000, v102
	v_fmamk_f32 v132, v128, 0xbc800000, v100
	v_mul_f32_e32 v133, v133, v133
	v_mul_f32_e32 v131, v131, v131
	v_fmac_f32_e32 v133, v132, v132
	v_fmac_f32_e32 v131, v130, v130
	v_add_f32_e32 v130, v133, v131
	v_fmamk_f32 v131, v128, 0xbc800000, v127
	v_fmamk_f32 v133, v128, 0xbc800000, v125
	v_add_f32_e32 v129, v130, v129
	v_fmamk_f32 v130, v128, 0xbc800000, v126
	v_fmamk_f32 v132, v128, 0xbc800000, v124
	v_mul_f32_e32 v133, v133, v133
	v_mul_f32_e32 v131, v131, v131
	v_fmac_f32_e32 v133, v132, v132
	v_fmac_f32_e32 v131, v130, v130
	v_add_f32_e32 v130, v133, v131
	v_add_f32_e32 v129, v130, v129
	v_mov_b32_e32 v130, v129
	s_nop 1
	v_permlane16_swap_b32_e32 v129, v130
	s_waitcnt lgkmcnt(0)
	v_add_f32_e32 v129, v129, v130
	v_mov_b32_e32 v130, v129
	s_nop 1
	v_permlane32_swap_b32_e32 v129, v130
	s_and_saveexec_b64 s[12:13], s[4:5]
	s_cbranch_execz .LBB0_707
	v_mul_f32_e32 v128, 0x3c800000, v128
	s_waitcnt lgkmcnt(0)
	v_add_f32_e32 v129, v129, v130
	ds_write_b64 v233, v[128:129] offset:5120
.LBB0_707:
	s_or_b64 exec, exec, s[12:13]
	v_mov_b32_e32 v128, v117
	v_mov_b32_e32 v129, v118
	s_waitcnt lgkmcnt(0)
	v_mov_b32_e32 v130, v116
	v_mov_b32_e32 v131, v119
	v_pk_add_f32 v[128:129], v[128:129], v[130:131]
	v_mov_b32_e32 v130, v109
	v_mov_b32_e32 v131, v110
	v_mov_b32_e32 v132, v108
	v_mov_b32_e32 v133, v111
	v_pk_add_f32 v[130:131], v[130:131], v[132:133]
	v_add_f32_e32 v128, v128, v129
	v_pk_add_f32 v[130:131], v[130:131], v[130:131] op_sel_hi:[0,1]
	v_add_f32_e32 v129, 0, v128
	v_add_f32_e32 v133, v96, v97
	v_add_f32_e32 v135, v98, v99
	v_mov_b32_e32 v132, v104
	v_mov_b32_e32 v134, v105
	v_mov_b32_e32 v130, v106
	v_mov_b32_e32 v128, v107
	v_pk_add_f32 v[132:133], v[132:133], v[134:135]
	v_pk_add_f32 v[128:129], v[130:131], v[128:129]
	s_nop 0
	v_pk_add_f32 v[128:129], v[132:133], v[128:129]
	s_nop 0
	v_add_f32_e32 v128, v128, v129
	v_mov_b32_e32 v129, v128
	s_nop 1
	v_permlane16_swap_b32_e32 v128, v129
	s_waitcnt lgkmcnt(0)
	v_add_f32_e32 v128, v128, v129
	v_mov_b32_e32 v129, v128
	s_nop 1
	v_permlane32_swap_b32_e32 v128, v129
	s_waitcnt lgkmcnt(0)
	v_add_f32_e32 v128, v128, v129
	v_fmamk_f32 v130, v128, 0xbc800000, v119
	v_fmamk_f32 v132, v128, 0xbc800000, v117
	v_fmamk_f32 v129, v128, 0xbc800000, v118
	v_fmamk_f32 v131, v128, 0xbc800000, v116
	v_mul_f32_e32 v132, v132, v132
	v_mul_f32_e32 v130, v130, v130
	v_fmac_f32_e32 v132, v131, v131
	v_fmac_f32_e32 v130, v129, v129
	v_fmamk_f32 v131, v128, 0xbc800000, v111
	v_fmamk_f32 v133, v128, 0xbc800000, v109
	v_add_f32_e32 v129, v132, v130
	v_fmamk_f32 v130, v128, 0xbc800000, v110
	v_fmamk_f32 v132, v128, 0xbc800000, v108
	v_mul_f32_e32 v133, v133, v133
	v_mul_f32_e32 v131, v131, v131
	v_fmac_f32_e32 v133, v132, v132
	v_fmac_f32_e32 v131, v130, v130
	v_add_f32_e32 v130, v133, v131
	v_fmamk_f32 v131, v128, 0xbc800000, v99
	v_fmamk_f32 v133, v128, 0xbc800000, v97
	v_add_f32_e32 v129, v129, v130
	v_fmamk_f32 v130, v128, 0xbc800000, v98
	v_fmamk_f32 v132, v128, 0xbc800000, v96
	v_mul_f32_e32 v133, v133, v133
	v_mul_f32_e32 v131, v131, v131
	v_fmac_f32_e32 v133, v132, v132
	v_fmac_f32_e32 v131, v130, v130
	v_add_f32_e32 v130, v133, v131
	v_fmamk_f32 v131, v128, 0xbc800000, v107
	v_fmamk_f32 v133, v128, 0xbc800000, v105
	v_add_f32_e32 v129, v130, v129
	v_fmamk_f32 v130, v128, 0xbc800000, v106
	v_fmamk_f32 v132, v128, 0xbc800000, v104
	v_mul_f32_e32 v133, v133, v133
	v_mul_f32_e32 v131, v131, v131
	v_fmac_f32_e32 v133, v132, v132
	v_fmac_f32_e32 v131, v130, v130
	v_add_f32_e32 v130, v133, v131
	v_add_f32_e32 v129, v130, v129
	v_mov_b32_e32 v130, v129
	s_nop 1
	v_permlane16_swap_b32_e32 v129, v130
	s_waitcnt lgkmcnt(0)
	v_add_f32_e32 v129, v129, v130
	v_mov_b32_e32 v130, v129
	s_nop 1
	v_permlane32_swap_b32_e32 v129, v130
	s_and_saveexec_b64 s[12:13], s[4:5]
	s_cbranch_execz .LBB0_709
	v_mul_f32_e32 v128, 0x3c800000, v128
	s_waitcnt lgkmcnt(0)
	v_add_f32_e32 v129, v129, v130
	ds_write_b64 v233, v[128:129] offset:5632
